# peel + per-unit scheduler divide replaced by shift/mask fast path (group size 8) in the three GEMM unit loops
# speedup vs baseline: 1.0022x; 1.0022x over previous
; #define PG8_STAGE(bufoff, gbase, voff) do { _Pragma("unroll") for (int _i = 0; _i < 2; ++_i) \
;         __builtin_amdgcn_global_load_lds((const unsigned*)((const char*)(gbase) + (voff)[_i]), (PG8_LAS unsigned*)(lds + (bufoff) + ldsw + _i * 8192), 16, 0, 0); } while (0)
; #define PG8_LDA(dst, b, h) do { _Pragma("unroll") for (int m = 0; m < 4; ++m) _Pragma("unroll") for (int k = 0; k < 2; ++k) dst[m][k] = *(const PG8_LAS bf16x8*)(lds + PG8_SA(b, h) + aoff + m * 2048 + k * 1024); } while (0)
; #define PG8_LDB(dst, b, h) do { _Pragma("unroll") for (int n = 0; n < 2; ++n) _Pragma("unroll") for (int k = 0; k < 2; ++k) dst[n][k] = *(const PG8_LAS bf16x8*)(lds + PG8_SB(b, h) + boff + n * 2048 + k * 1024); } while (0)
; #define PG8_BAR __builtin_amdgcn_s_barrier()
;     __host__ __device__ bool next(int i, Unit& u) const {
;         const long L = (long)i * G + c; if (L >= nwg) return false;
;         int wgid = (int)L; { const int q = nwg / NXCD, r = nwg % NXCD, xcd = wgid % NXCD, off = wgid / NXCD; wgid = (xcd < r ? xcd * (q + 1) : r * (q + 1) + (xcd - r) * q) + off; }
;         const int nig = WGM * nN, gid = wgid / nig, fm = gid * WGM, gsz = (nM - fm) < WGM ? (nM - fm) : WGM;
;         u.pm = fm + ((wgid % nig) % gsz); u.pn = (wgid % nig) / gsz; return true;
;     }
; template <class Epi, class Sched, bool ALIGN_EPI = false, bool SP2 = false>
; __device__ __forceinline__ void gemm_phase(PG8_LAS unsigned char* lds, const Gemm g, const Sched& S, const Epi& E) {
;     ...
;         const bool has_next = S.next(ui + 1, nxt);
;         const char* nA = has_next ? (const char*)g.A + (size_t)nxt.pm * tstep : cA; const char* nB = has_next ? (const char*)g.Bt + (size_t)nxt.pn * tstep : cB;
;         for (int t = 0; t < nt; t += 2) {
;             const bool last = (t == nt - 2);
;             const char* a1 = cA + (size_t)(t + 1) * kstepA;
;             const char* a2 = last ? nA : cA + (size_t)(t + 2) * kstepA; const char* b2 = last ? nB : cB + (size_t)(t + 2) * kstep;
;             const char* a3 = a2 + kstepA; const char* b3 = b2 + kstep;
;             if (last && has_next) S.a_ready(nxt);
;             if constexpr (SP2) {
;             PG8_LDB(B0, 0, 0); PG8_LDB(B1, 0, 1); PG8_SCHED; PG8_LDA(At, 0, 0); PG8_STAGE(PG8_SA(1, 1), a1 + hstep, voffA);
;             PG8_WAIT_V(8); PG8_WAIT_L(0); PG8_BAR; PG8_MMA(0, 0, At, B0); PG8_MMA(0, 1, At, B1); PG8_BAR; PG8_SCHED;
.LBB0_235:
	s_add_i32 s66, s21, 1
	s_mul_i32 s2, s66, s15
	s_mul_hi_u32 s3, s66, s14
	s_add_i32 s3, s3, s2
	s_mul_i32 s2, s66, s14
	s_add_u32 s2, s2, s16
	s_addc_u32 s3, s3, s17
	v_mov_b64_e32 v[2:3], s[48:49]
	v_cmp_ge_i64_e32 vcc, s[2:3], v[2:3]
	v_cmp_lt_i64_e64 s[40:41], s[2:3], v[2:3]
	s_cbranch_vccnz .LBB0_237
	s_ashr_i32 s3, s2, 31
	s_lshr_b32 s3, s3, 29
	s_add_i32 s3, s2, s3
	s_ashr_i32 s8, s3, 3
	s_and_b32 s3, s3, -8
	s_sub_i32 s2, s2, s3
	s_cmp_lt_i32 s2, 0
	s_cselect_b32 s3, s37, s29
	s_mul_i32 s2, s3, s2
	s_add_i32 s2, s2, s8
	s_abs_i32 s8, s2
	s_mul_hi_u32 s9, s8, s50
	s_mul_i32 s10, s9, s18
	s_sub_i32 s8, s8, s10
	s_ashr_i32 s3, s2, 31
	s_add_i32 s10, s9, 1
	s_sub_i32 s11, s8, s18
	s_cmp_ge_u32 s8, s18
	s_cselect_b32 s9, s10, s9
	s_cselect_b32 s8, s11, s8
	s_add_i32 s10, s9, 1
	s_cmp_ge_u32 s8, s18
	s_cselect_b32 s8, s10, s9
	s_xor_b32 s8, s8, s3
	s_sub_i32 s3, s8, s3
	s_lshl_b32 s9, s3, 3
	s_sub_i32 s8, s19, s9
	s_min_i32 s10, s8, 8
	s_cmp_lg_u32 s10, 8
	s_cbranch_scc1 .Lslowdiv_0
	s_mul_i32 s3, s3, s18
	s_sub_i32 s2, s2, s3
	s_lshr_b32 s8, s2, 3
	s_and_b32 s2, s2, 7
	s_add_i32 s10, s2, s9
	s_branch .Lfastdiv_done_0
.Lslowdiv_0:
	s_abs_i32 s8, s10
	v_cvt_f32_u32_e32 v2, s8
	s_sub_i32 s12, 0, s8
	s_mul_i32 s3, s3, s18
	s_sub_i32 s2, s2, s3
	v_rcp_iflag_f32_e32 v2, v2
	s_abs_i32 s11, s2
	s_xor_b32 s3, s2, s10
	s_ashr_i32 s3, s3, 31
	v_mul_f32_e32 v2, 0x4f7ffffe, v2
	v_cvt_u32_f32_e32 v2, v2
	s_nop 0
	v_readfirstlane_b32 s13, v2
	s_mul_i32 s12, s12, s13
	s_mul_hi_u32 s12, s13, s12
	s_add_i32 s13, s13, s12
	s_mul_hi_u32 s12, s11, s13
	s_mul_i32 s13, s12, s8
	s_sub_i32 s11, s11, s13
	s_add_i32 s13, s12, 1
	s_sub_i32 s42, s11, s8
	s_cmp_ge_u32 s11, s8
	s_cselect_b32 s12, s13, s12
	s_cselect_b32 s11, s42, s11
	s_add_i32 s13, s12, 1
	s_cmp_ge_u32 s11, s8
	s_cselect_b32 s8, s13, s12
	s_xor_b32 s8, s8, s3
	s_sub_i32 s8, s8, s3
	s_mul_i32 s3, s8, s10
	s_sub_i32 s2, s2, s3
	s_add_i32 s10, s2, s9
.Lfastdiv_done_0:
.LBB0_237:
	s_ashr_i32 s11, s10, 31
	s_lshl_b64 s[2:3], s[10:11], 19
	s_add_u32 s12, s52, s2
	s_addc_u32 s13, s53, s3
	s_and_b64 s[2:3], s[40:41], exec
	s_cselect_b32 s11, s13, s25
	s_cselect_b32 s67, s12, s24
	s_ashr_i32 s9, s8, 31
	s_lshl_b64 s[2:3], s[8:9], 19
	s_add_u32 s44, s54, s2
	s_addc_u32 s45, s55, s3
	s_and_b64 s[2:3], s[40:41], exec
	s_cselect_b32 s9, s45, s27
	s_cselect_b32 s68, s44, s26
	s_add_u32 s69, s26, 0x100
	s_addc_u32 s70, s27, 0
	s_mov_b32 s71, -2
	s_add_u32 s2, s24, 0x8000
	s_addc_u32 s3, s25, 0
	s_cmp_eq_u32 s71, 12
	s_cselect_b32 s46, s67, s2
	s_cselect_b32 s47, s11, s3
	s_cselect_b32 s42, s68, s69
	s_cselect_b32 s43, s9, s70
	s_add_u32 s26, s46, 0x4000
	s_addc_u32 s27, s47, 0
	v_add_u32_e32 v148, s76, v150
	s_add_i32 s72, 0, 0x14000
	ds_read_b128 v[144:147], v148
	ds_read_b128 v[160:163], v148 offset:1024
	ds_read_b128 v[164:167], v148 offset:2048
	ds_read_b128 v[168:171], v148 offset:3072
	v_add_u32_e32 v148, s72, v150
	ds_read_b128 v[172:175], v148
	ds_read_b128 v[176:179], v148 offset:1024
	ds_read_b128 v[180:183], v148 offset:2048
	ds_read_b128 v[184:187], v148 offset:3072
	v_lshl_add_u64 v[148:149], s[24:25], 0, v[142:143]
	s_add_i32 m0, s23, 0xc000
	ds_read_b128 v[188:191], v152
	ds_read_b128 v[206:209], v152 offset:1024
	ds_read_b128 v[210:213], v152 offset:2048
	ds_read_b128 v[214:217], v152 offset:3072
	ds_read_b128 v[218:221], v152 offset:4096
	ds_read_b128 v[222:225], v152 offset:5120
	ds_read_b128 v[226:229], v152 offset:6144
	ds_read_b128 v[230:233], v152 offset:7168
	global_load_lds_dwordx4 v[148:149], off
	v_lshl_add_u64 v[148:149], s[24:25], 0, v[140:141]
	s_add_i32 m0, s23, 0xe000
	s_nop 0
	global_load_lds_dwordx4 v[148:149], off
	s_waitcnt vmcnt(8)
	s_waitcnt lgkmcnt(0)
	s_barrier
	v_mfma_f32_16x16x32_bf16 v[126:129], v[144:147], v[188:191], 0
	v_mfma_f32_16x16x32_bf16 v[126:129], v[160:163], v[206:209], v[126:129]
	v_mfma_f32_16x16x32_bf16 v[122:125], v[168:171], v[206:209], 0
	v_mfma_f32_16x16x32_bf16 v[122:125], v[164:167], v[188:191], v[122:125]
	v_mfma_f32_16x16x32_bf16 v[106:109], v[164:167], v[210:213], 0
	v_mfma_f32_16x16x32_bf16 v[106:109], v[168:171], v[214:217], v[106:109]
	v_mfma_f32_16x16x32_bf16 v[110:113], v[160:163], v[214:217], 0
	v_mfma_f32_16x16x32_bf16 v[110:113], v[144:147], v[210:213], v[110:113]
	v_mfma_f32_16x16x32_bf16 v[94:97], v[144:147], v[218:221], 0
	v_mfma_f32_16x16x32_bf16 v[94:97], v[160:163], v[222:225], v[94:97]
	v_mfma_f32_16x16x32_bf16 v[90:93], v[168:171], v[222:225], 0
	v_mfma_f32_16x16x32_bf16 v[90:93], v[164:167], v[218:221], v[90:93]
	v_mfma_f32_16x16x32_bf16 v[74:77], v[164:167], v[226:229], 0
	v_mfma_f32_16x16x32_bf16 v[74:77], v[168:171], v[230:233], v[74:77]
	v_mfma_f32_16x16x32_bf16 v[78:81], v[160:163], v[230:233], 0
	v_mfma_f32_16x16x32_bf16 v[78:81], v[144:147], v[226:229], v[78:81]
	v_mfma_f32_16x16x32_bf16 v[118:121], v[172:175], v[188:191], 0
	v_mfma_f32_16x16x32_bf16 v[118:121], v[176:179], v[206:209], v[118:121]
	v_mfma_f32_16x16x32_bf16 v[114:117], v[184:187], v[206:209], 0
	v_mfma_f32_16x16x32_bf16 v[114:117], v[180:183], v[188:191], v[114:117]
	v_mfma_f32_16x16x32_bf16 v[98:101], v[180:183], v[210:213], 0
	v_mfma_f32_16x16x32_bf16 v[98:101], v[184:187], v[214:217], v[98:101]
	v_mfma_f32_16x16x32_bf16 v[102:105], v[176:179], v[214:217], 0
	v_mfma_f32_16x16x32_bf16 v[102:105], v[172:175], v[210:213], v[102:105]
	v_mfma_f32_16x16x32_bf16 v[86:89], v[172:175], v[218:221], 0
	v_mfma_f32_16x16x32_bf16 v[86:89], v[176:179], v[222:225], v[86:89]
	v_mfma_f32_16x16x32_bf16 v[82:85], v[184:187], v[222:225], 0
	v_mfma_f32_16x16x32_bf16 v[82:85], v[180:183], v[218:221], v[82:85]
	v_mfma_f32_16x16x32_bf16 v[66:69], v[180:183], v[226:229], 0
	v_mfma_f32_16x16x32_bf16 v[66:69], v[184:187], v[230:233], v[66:69]
	v_mfma_f32_16x16x32_bf16 v[70:73], v[176:179], v[230:233], 0
	v_mfma_f32_16x16x32_bf16 v[70:73], v[172:175], v[226:229], v[70:73]
	s_barrier
; #define PG8_STAGE(bufoff, gbase, voff) do { _Pragma("unroll") for (int _i = 0; _i < 2; ++_i) \
;         __builtin_amdgcn_global_load_lds((const unsigned*)((const char*)(gbase) + (voff)[_i]), (PG8_LAS unsigned*)(lds + (bufoff) + ldsw + _i * 8192), 16, 0, 0); } while (0)
; #define PG8_LDA(dst, b, h) do { _Pragma("unroll") for (int m = 0; m < 4; ++m) _Pragma("unroll") for (int k = 0; k < 2; ++k) dst[m][k] = *(const PG8_LAS bf16x8*)(lds + PG8_SA(b, h) + aoff + m * 2048 + k * 1024); } while (0)
; #define PG8_LDB(dst, b, h) do { _Pragma("unroll") for (int n = 0; n < 2; ++n) _Pragma("unroll") for (int k = 0; k < 2; ++k) dst[n][k] = *(const PG8_LAS bf16x8*)(lds + PG8_SB(b, h) + boff + n * 2048 + k * 1024); } while (0)
; #define PG8_MMA(ai, bj, At, Bt) do { __builtin_amdgcn_s_setprio(1); _Pragma("unroll") for (int m = 0; m < 4; ++m) _Pragma("unroll") for (int n = 0; n < 2; ++n) _Pragma("unroll") for (int k = 0; k < 2; ++k) \
;         acc[ai][bj][m][n] = __builtin_amdgcn_mfma_f32_16x16x32_bf16(Bt[n][k], At[m][k], acc[ai][bj][m][n], 0, 0, 0); __builtin_amdgcn_s_setprio(0); } while (0)
; #define PG8_WAIT_V(n) asm volatile("s_waitcnt vmcnt(" #n ")" ::: "memory")
; #define PG8_WAIT_L(n) asm volatile("s_waitcnt lgkmcnt(" #n ")" ::: "memory")
; #define PG8_BAR __builtin_amdgcn_s_barrier()
; #define PG8_SCHED __builtin_amdgcn_sched_barrier(0)
; template <class Epi, class Sched, bool ALIGN_EPI = false, bool SP2 = false>
; __device__ __forceinline__ void gemm_phase(PG8_LAS unsigned char* lds, const Gemm g, const Sched& S, const Epi& E) {
;     ...
;             PG8_LDA(At, 0, 1); PG8_STAGE(PG8_SB(0, 0), b2, voffB); PG8_STAGE(PG8_SB(0, 1), b2 + hstep, voffB); PG8_STAGE(PG8_SA(0, 0), a2, voffA);
;             PG8_WAIT_V(8); PG8_WAIT_L(0); PG8_BAR; PG8_MMA(1, 0, At, B0); PG8_MMA(1, 1, At, B1); PG8_BAR; PG8_SCHED;
;             PG8_LDB(B0, 1, 0); PG8_LDB(B1, 1, 1); PG8_SCHED; PG8_LDA(At, 1, 0); PG8_STAGE(PG8_SA(0, 1), a2 + hstep, voffA);
;             PG8_WAIT_V(8); PG8_WAIT_L(0); PG8_BAR; PG8_MMA(0, 0, At, B0); PG8_MMA(0, 1, At, B1); PG8_BAR; PG8_SCHED;
	s_add_i32 s24, s76, s51
	v_lshl_add_u64 v[148:149], s[42:43], 0, v[132:133]
	s_mov_b32 m0, s24
	ds_read_b128 v[188:191], v152 offset:16384
	ds_read_b128 v[206:209], v152 offset:17408
	ds_read_b128 v[210:213], v152 offset:18432
	ds_read_b128 v[214:217], v152 offset:19456
	ds_read_b128 v[218:221], v152 offset:20480
	ds_read_b128 v[222:225], v152 offset:21504
	ds_read_b128 v[226:229], v152 offset:22528
	ds_read_b128 v[230:233], v152 offset:23552
	global_load_lds_dwordx4 v[148:149], off
	s_add_i32 m0, s24, 0x2000
	s_add_u32 s24, s42, 0x40000
	v_lshl_add_u64 v[234:235], s[42:43], 0, v[136:137]
	s_addc_u32 s25, s43, 0
	s_add_i32 s72, s72, s51
	global_load_lds_dwordx4 v[234:235], off
	v_lshl_add_u64 v[236:237], s[24:25], 0, v[132:133]
	s_mov_b32 m0, s72
	s_nop 0
	global_load_lds_dwordx4 v[236:237], off
	v_lshl_add_u64 v[236:237], s[24:25], 0, v[136:137]
	s_add_i32 m0, s72, 0x2000
	s_nop 0
	global_load_lds_dwordx4 v[236:237], off
	v_lshl_add_u64 v[236:237], s[46:47], 0, v[130:131]
	s_mov_b32 m0, s23
	s_nop 0
	global_load_lds_dwordx4 v[236:237], off
	v_lshl_add_u64 v[236:237], s[46:47], 0, v[134:135]
	s_mov_b32 m0, s56
	s_nop 0
	global_load_lds_dwordx4 v[236:237], off
	s_waitcnt vmcnt(8)
	s_waitcnt lgkmcnt(0)
	s_barrier
	v_mfma_f32_16x16x32_bf16 v[62:65], v[144:147], v[188:191], 0
	v_mfma_f32_16x16x32_bf16 v[62:65], v[160:163], v[206:209], v[62:65]
	v_mfma_f32_16x16x32_bf16 v[58:61], v[168:171], v[206:209], 0
	v_mfma_f32_16x16x32_bf16 v[58:61], v[164:167], v[188:191], v[58:61]
	v_mfma_f32_16x16x32_bf16 v[42:45], v[164:167], v[210:213], 0
	v_mfma_f32_16x16x32_bf16 v[42:45], v[168:171], v[214:217], v[42:45]
	v_mfma_f32_16x16x32_bf16 v[46:49], v[160:163], v[214:217], 0
	v_mfma_f32_16x16x32_bf16 v[46:49], v[144:147], v[210:213], v[46:49]
	v_mfma_f32_16x16x32_bf16 v[30:33], v[144:147], v[218:221], 0
	v_mfma_f32_16x16x32_bf16 v[30:33], v[160:163], v[222:225], v[30:33]
	v_mfma_f32_16x16x32_bf16 v[26:29], v[168:171], v[222:225], 0
	v_mfma_f32_16x16x32_bf16 v[26:29], v[164:167], v[218:221], v[26:29]
	v_mfma_f32_16x16x32_bf16 v[10:13], v[164:167], v[226:229], 0
	v_mfma_f32_16x16x32_bf16 v[10:13], v[168:171], v[230:233], v[10:13]
	v_mfma_f32_16x16x32_bf16 v[14:17], v[160:163], v[230:233], 0
	v_mfma_f32_16x16x32_bf16 v[14:17], v[144:147], v[226:229], v[14:17]
	v_mfma_f32_16x16x32_bf16 v[54:57], v[172:175], v[188:191], 0
	v_mfma_f32_16x16x32_bf16 v[54:57], v[176:179], v[206:209], v[54:57]
	v_mfma_f32_16x16x32_bf16 v[50:53], v[184:187], v[206:209], 0
	v_mfma_f32_16x16x32_bf16 v[50:53], v[180:183], v[188:191], v[50:53]
	v_mfma_f32_16x16x32_bf16 v[34:37], v[180:183], v[210:213], 0
	v_mfma_f32_16x16x32_bf16 v[34:37], v[184:187], v[214:217], v[34:37]
	v_mfma_f32_16x16x32_bf16 v[38:41], v[176:179], v[214:217], 0
	v_mfma_f32_16x16x32_bf16 v[38:41], v[172:175], v[210:213], v[38:41]
	v_mfma_f32_16x16x32_bf16 v[22:25], v[172:175], v[218:221], 0
	v_mfma_f32_16x16x32_bf16 v[22:25], v[176:179], v[222:225], v[22:25]
	v_mfma_f32_16x16x32_bf16 v[18:21], v[184:187], v[222:225], 0
	v_mfma_f32_16x16x32_bf16 v[18:21], v[180:183], v[218:221], v[18:21]
	v_mfma_f32_16x16x32_bf16 v[2:5], v[180:183], v[226:229], 0
	v_mfma_f32_16x16x32_bf16 v[2:5], v[184:187], v[230:233], v[2:5]
	v_mfma_f32_16x16x32_bf16 v[6:9], v[176:179], v[230:233], 0
	v_mfma_f32_16x16x32_bf16 v[6:9], v[172:175], v[226:229], v[6:9]
	s_barrier
	s_add_i32 s72, 0, 0x18000
	v_add_u32_e32 v153, s72, v150
	s_add_i32 s73, 0, 0x1c000
	ds_read_b128 v[144:147], v153
	ds_read_b128 v[160:163], v153 offset:1024
	ds_read_b128 v[164:167], v153 offset:2048
	ds_read_b128 v[168:171], v153 offset:3072
	v_add_u32_e32 v153, s73, v150
	ds_read_b128 v[172:175], v153
	ds_read_b128 v[176:179], v153 offset:1024
	ds_read_b128 v[180:183], v153 offset:2048
	ds_read_b128 v[184:187], v153 offset:3072
	s_add_u32 s24, s46, 0x40000
	s_addc_u32 s25, s47, 0
	s_mov_b32 m0, s57
	v_lshl_add_u64 v[236:237], s[24:25], 0, v[130:131]
	ds_read_b128 v[188:191], v152 offset:32768
	ds_read_b128 v[206:209], v152 offset:33792
	ds_read_b128 v[210:213], v152 offset:34816
	ds_read_b128 v[214:217], v152 offset:35840
	ds_read_b128 v[218:221], v152 offset:36864
	ds_read_b128 v[222:225], v152 offset:37888
	ds_read_b128 v[226:229], v152 offset:38912
	ds_read_b128 v[230:233], v152 offset:39936
	global_load_lds_dwordx4 v[236:237], off
	v_lshl_add_u64 v[236:237], s[24:25], 0, v[134:135]
	s_mov_b32 m0, s58
	s_nop 0
	global_load_lds_dwordx4 v[236:237], off
	s_waitcnt vmcnt(8)
	s_waitcnt lgkmcnt(0)
	s_barrier
; #define PG8_STAGE(bufoff, gbase, voff) do { _Pragma("unroll") for (int _i = 0; _i < 2; ++_i) \
;         __builtin_amdgcn_global_load_lds((const unsigned*)((const char*)(gbase) + (voff)[_i]), (PG8_LAS unsigned*)(lds + (bufoff) + ldsw + _i * 8192), 16, 0, 0); } while (0)
; #define PG8_LDA(dst, b, h) do { _Pragma("unroll") for (int m = 0; m < 4; ++m) _Pragma("unroll") for (int k = 0; k < 2; ++k) dst[m][k] = *(const PG8_LAS bf16x8*)(lds + PG8_SA(b, h) + aoff + m * 2048 + k * 1024); } while (0)
; #define PG8_MMA(ai, bj, At, Bt) do { __builtin_amdgcn_s_setprio(1); _Pragma("unroll") for (int m = 0; m < 4; ++m) _Pragma("unroll") for (int n = 0; n < 2; ++n) _Pragma("unroll") for (int k = 0; k < 2; ++k) \
;         acc[ai][bj][m][n] = __builtin_amdgcn_mfma_f32_16x16x32_bf16(Bt[n][k], At[m][k], acc[ai][bj][m][n], 0, 0, 0); __builtin_amdgcn_s_setprio(0); } while (0)
; #define PG8_WAIT_V(n) asm volatile("s_waitcnt vmcnt(" #n ")" ::: "memory")
; #define PG8_WAIT_L(n) asm volatile("s_waitcnt lgkmcnt(" #n ")" ::: "memory")
; #define PG8_BAR __builtin_amdgcn_s_barrier()
; #define PG8_SCHED __builtin_amdgcn_sched_barrier(0)
; template <class Epi, class Sched, bool ALIGN_EPI = false, bool SP2 = false>
; __device__ __forceinline__ void gemm_phase(PG8_LAS unsigned char* lds, const Gemm g, const Sched& S, const Epi& E) {
;     ...
;             PG8_WAIT_V(8); PG8_WAIT_L(0); PG8_BAR; PG8_MMA(0, 0, At, B0); PG8_MMA(0, 1, At, B1); PG8_BAR; PG8_SCHED;
;             PG8_LDA(At, 1, 1); PG8_STAGE(PG8_SB(1, 0), b3, voffB); PG8_STAGE(PG8_SB(1, 1), b3 + hstep, voffB); PG8_STAGE(PG8_SA(1, 0), a3, voffA);
;             PG8_WAIT_V(8); PG8_WAIT_L(0); PG8_BAR; PG8_MMA(1, 0, At, B0); PG8_MMA(1, 1, At, B1); PG8_BAR; PG8_SCHED;
	v_mfma_f32_16x16x32_bf16 v[126:129], v[144:147], v[188:191], v[126:129]
	v_mfma_f32_16x16x32_bf16 v[126:129], v[160:163], v[206:209], v[126:129]
	v_mfma_f32_16x16x32_bf16 v[122:125], v[168:171], v[206:209], v[122:125]
	v_mfma_f32_16x16x32_bf16 v[122:125], v[164:167], v[188:191], v[122:125]
	v_mfma_f32_16x16x32_bf16 v[106:109], v[164:167], v[210:213], v[106:109]
	v_mfma_f32_16x16x32_bf16 v[106:109], v[168:171], v[214:217], v[106:109]
	v_mfma_f32_16x16x32_bf16 v[110:113], v[160:163], v[214:217], v[110:113]
	v_mfma_f32_16x16x32_bf16 v[110:113], v[144:147], v[210:213], v[110:113]
	v_mfma_f32_16x16x32_bf16 v[94:97], v[144:147], v[218:221], v[94:97]
	v_mfma_f32_16x16x32_bf16 v[94:97], v[160:163], v[222:225], v[94:97]
	v_mfma_f32_16x16x32_bf16 v[90:93], v[168:171], v[222:225], v[90:93]
	v_mfma_f32_16x16x32_bf16 v[90:93], v[164:167], v[218:221], v[90:93]
	v_mfma_f32_16x16x32_bf16 v[74:77], v[164:167], v[226:229], v[74:77]
	v_mfma_f32_16x16x32_bf16 v[74:77], v[168:171], v[230:233], v[74:77]
	v_mfma_f32_16x16x32_bf16 v[78:81], v[160:163], v[230:233], v[78:81]
	v_mfma_f32_16x16x32_bf16 v[78:81], v[144:147], v[226:229], v[78:81]
	v_mfma_f32_16x16x32_bf16 v[118:121], v[172:175], v[188:191], v[118:121]
	v_mfma_f32_16x16x32_bf16 v[118:121], v[176:179], v[206:209], v[118:121]
	v_mfma_f32_16x16x32_bf16 v[114:117], v[184:187], v[206:209], v[114:117]
	v_mfma_f32_16x16x32_bf16 v[114:117], v[180:183], v[188:191], v[114:117]
	v_mfma_f32_16x16x32_bf16 v[98:101], v[180:183], v[210:213], v[98:101]
	v_mfma_f32_16x16x32_bf16 v[98:101], v[184:187], v[214:217], v[98:101]
	v_mfma_f32_16x16x32_bf16 v[102:105], v[176:179], v[214:217], v[102:105]
	v_mfma_f32_16x16x32_bf16 v[102:105], v[172:175], v[210:213], v[102:105]
	v_mfma_f32_16x16x32_bf16 v[86:89], v[172:175], v[218:221], v[86:89]
	v_mfma_f32_16x16x32_bf16 v[86:89], v[176:179], v[222:225], v[86:89]
	v_mfma_f32_16x16x32_bf16 v[82:85], v[184:187], v[222:225], v[82:85]
	v_mfma_f32_16x16x32_bf16 v[82:85], v[180:183], v[218:221], v[82:85]
	v_mfma_f32_16x16x32_bf16 v[66:69], v[180:183], v[226:229], v[66:69]
	v_mfma_f32_16x16x32_bf16 v[66:69], v[184:187], v[230:233], v[66:69]
	v_mfma_f32_16x16x32_bf16 v[70:73], v[176:179], v[230:233], v[70:73]
	v_mfma_f32_16x16x32_bf16 v[70:73], v[172:175], v[226:229], v[70:73]
	s_barrier
	s_add_i32 s24, s72, s51
	v_lshl_add_u64 v[148:149], v[148:149], 0, s[38:39]
	s_mov_b32 m0, s24
	ds_read_b128 v[188:191], v152 offset:49152
	ds_read_b128 v[206:209], v152 offset:50176
	ds_read_b128 v[210:213], v152 offset:51200
	ds_read_b128 v[214:217], v152 offset:52224
	ds_read_b128 v[218:221], v152 offset:53248
	ds_read_b128 v[222:225], v152 offset:54272
	ds_read_b128 v[226:229], v152 offset:55296
	ds_read_b128 v[230:233], v152 offset:56320
	global_load_lds_dwordx4 v[148:149], off
	s_add_i32 m0, s24, 0x2000
	s_add_u32 s24, s42, 0x40080
	v_lshl_add_u64 v[148:149], v[234:235], 0, s[38:39]
	s_addc_u32 s25, s43, 0
	s_add_i32 s42, s73, s51
	global_load_lds_dwordx4 v[148:149], off
	v_lshl_add_u64 v[148:149], s[24:25], 0, v[132:133]
	s_mov_b32 m0, s42
	s_nop 0
	global_load_lds_dwordx4 v[148:149], off
	v_lshl_add_u64 v[148:149], s[24:25], 0, v[136:137]
	s_add_i32 m0, s42, 0x2000
	s_nop 0
	global_load_lds_dwordx4 v[148:149], off
	v_lshl_add_u64 v[148:149], s[26:27], 0, v[130:131]
	s_mov_b32 m0, s64
	s_nop 0
	global_load_lds_dwordx4 v[148:149], off
	v_lshl_add_u64 v[148:149], s[26:27], 0, v[134:135]
	s_mov_b32 m0, s65
	s_nop 0
	global_load_lds_dwordx4 v[148:149], off
	s_waitcnt vmcnt(8)
	s_waitcnt lgkmcnt(0)
	s_barrier
	v_mfma_f32_16x16x32_bf16 v[62:65], v[144:147], v[188:191], v[62:65]
	v_mfma_f32_16x16x32_bf16 v[62:65], v[160:163], v[206:209], v[62:65]
	v_mfma_f32_16x16x32_bf16 v[58:61], v[168:171], v[206:209], v[58:61]
	v_mfma_f32_16x16x32_bf16 v[58:61], v[164:167], v[188:191], v[58:61]
	v_mfma_f32_16x16x32_bf16 v[42:45], v[164:167], v[210:213], v[42:45]
	v_mfma_f32_16x16x32_bf16 v[42:45], v[168:171], v[214:217], v[42:45]
	v_mfma_f32_16x16x32_bf16 v[46:49], v[160:163], v[214:217], v[46:49]
	v_mfma_f32_16x16x32_bf16 v[46:49], v[144:147], v[210:213], v[46:49]
	v_mfma_f32_16x16x32_bf16 v[30:33], v[144:147], v[218:221], v[30:33]
	v_mfma_f32_16x16x32_bf16 v[30:33], v[160:163], v[222:225], v[30:33]
	v_mfma_f32_16x16x32_bf16 v[26:29], v[168:171], v[222:225], v[26:29]
	v_mfma_f32_16x16x32_bf16 v[26:29], v[164:167], v[218:221], v[26:29]
	v_mfma_f32_16x16x32_bf16 v[10:13], v[164:167], v[226:229], v[10:13]
	v_mfma_f32_16x16x32_bf16 v[10:13], v[168:171], v[230:233], v[10:13]
	v_mfma_f32_16x16x32_bf16 v[14:17], v[160:163], v[230:233], v[14:17]
	v_mfma_f32_16x16x32_bf16 v[14:17], v[144:147], v[226:229], v[14:17]
	v_mfma_f32_16x16x32_bf16 v[54:57], v[172:175], v[188:191], v[54:57]
	v_mfma_f32_16x16x32_bf16 v[54:57], v[176:179], v[206:209], v[54:57]
	v_mfma_f32_16x16x32_bf16 v[50:53], v[184:187], v[206:209], v[50:53]
	v_mfma_f32_16x16x32_bf16 v[50:53], v[180:183], v[188:191], v[50:53]
	v_mfma_f32_16x16x32_bf16 v[34:37], v[180:183], v[210:213], v[34:37]
	v_mfma_f32_16x16x32_bf16 v[34:37], v[184:187], v[214:217], v[34:37]
	v_mfma_f32_16x16x32_bf16 v[38:41], v[176:179], v[214:217], v[38:41]
	v_mfma_f32_16x16x32_bf16 v[38:41], v[172:175], v[210:213], v[38:41]
	v_mfma_f32_16x16x32_bf16 v[22:25], v[172:175], v[218:221], v[22:25]
	v_mfma_f32_16x16x32_bf16 v[22:25], v[176:179], v[222:225], v[22:25]
	v_mfma_f32_16x16x32_bf16 v[18:21], v[184:187], v[222:225], v[18:21]
	v_mfma_f32_16x16x32_bf16 v[18:21], v[180:183], v[218:221], v[18:21]
	v_mfma_f32_16x16x32_bf16 v[2:5], v[180:183], v[226:229], v[2:5]
	v_mfma_f32_16x16x32_bf16 v[2:5], v[184:187], v[230:233], v[2:5]
	v_mfma_f32_16x16x32_bf16 v[6:9], v[176:179], v[230:233], v[6:9]
	v_mfma_f32_16x16x32_bf16 v[6:9], v[172:175], v[226:229], v[6:9]
	s_barrier
	s_add_i32 s71, s71, 2
	s_add_u32 s69, s69, 0x100
	s_addc_u32 s70, s70, 0
	s_cmp_gt_u32 s71, 13
	s_mov_b64 s[24:25], s[2:3]
	s_cbranch_scc1 .Lpeel_exit_0

;     __host__ __device__ bool next(int i, Unit& u) const {
;     ...
;         int wgid = (int)L; { const int q = nwg / NXCD, r = nwg % NXCD, xcd = wgid % NXCD, off = wgid / NXCD; wgid = (xcd < r ? xcd * (q + 1) : r * (q + 1) + (xcd - r) * q) + off; }
;         const int nig = WGM * nN, gid = wgid / nig, fm = gid * WGM, gsz = (nM - fm) < WGM ? (nM - fm) : WGM;
;         u.pm = fm + ((wgid % nig) % gsz); u.pn = (wgid % nig) / gsz; return true;
; template <class Epi, class Sched, bool ALIGN_EPI = false, bool SP2 = false>
; __device__ __forceinline__ void gemm_phase(PG8_LAS unsigned char* lds, const Gemm g, const Sched& S, const Epi& E) {
;     ...
;         const char* nA = has_next ? (const char*)g.A + (size_t)nxt.pm * tstep : cA; const char* nB = has_next ? (const char*)g.Bt + (size_t)nxt.pn * tstep : cB;
.LBB0_304:
	s_ashr_i32 s2, s6, 3
	s_add_i32 s2, s13, s2
	s_ashr_i32 s3, s2, 31
	s_lshr_b32 s3, s3, 27
	s_add_i32 s3, s2, s3
	s_ashr_i32 s6, s3, 5
	s_lshl_b32 s6, s6, 3
	s_sub_i32 s7, s15, s6
	s_min_i32 s7, s7, 8
	s_cmp_lg_u32 s7, 8
	s_cbranch_scc1 .Lslowdiv_1
	s_andn2_b32 s3, s3, 31
	s_sub_i32 s2, s2, s3
	s_lshr_b32 s13, s2, 3
	s_and_b32 s2, s2, 7
	s_add_i32 s64, s6, s2
	s_branch .Lfastdiv_done_1
.Lslowdiv_1:
	s_abs_i32 s13, s7
	v_cvt_f32_u32_e32 v2, s13
	s_sub_i32 s45, 0, s13
	s_andn2_b32 s3, s3, 31
	s_sub_i32 s2, s2, s3
	v_rcp_iflag_f32_e32 v2, v2
	s_abs_i32 s3, s2
	s_xor_b32 s44, s2, s7
	s_ashr_i32 s44, s44, 31
	v_mul_f32_e32 v2, 0x4f7ffffe, v2
	v_cvt_u32_f32_e32 v2, v2
	s_nop 0
	v_readfirstlane_b32 s47, v2
	s_mul_i32 s45, s45, s47
	s_mul_hi_u32 s45, s47, s45
	s_add_i32 s47, s47, s45
	s_mul_hi_u32 s45, s3, s47
	s_mul_i32 s47, s45, s13
	s_sub_i32 s3, s3, s47
	s_add_i32 s48, s45, 1
	s_sub_i32 s47, s3, s13
	s_cmp_ge_u32 s3, s13
	s_cselect_b32 s45, s48, s45
	s_cselect_b32 s3, s47, s3
	s_add_i32 s47, s45, 1
	s_cmp_ge_u32 s3, s13
	s_cselect_b32 s3, s47, s45
	s_xor_b32 s3, s3, s44
	s_sub_i32 s13, s3, s44
	s_mul_i32 s3, s13, s7
	s_sub_i32 s2, s2, s3
	s_add_i32 s64, s6, s2
.Lfastdiv_done_1:
.LBB0_305:
	s_nop 0
	v_cndmask_b32_e64 v2, 0, 1, s[8:9]
	v_cmp_ne_u32_e64 s[6:7], 1, v2
	s_andn2_b64 vcc, exec, s[8:9]
	s_mov_b64 s[8:9], s[26:27]
	s_cbranch_vccnz .LBB0_307
	s_mul_i32 s3, s37, s64
	s_mul_hi_i32 s2, s37, s64
	s_add_u32 s8, s18, s3
	s_addc_u32 s9, s17, s2

; #define PG8_STAGE(bufoff, gbase, voff) do { _Pragma("unroll") for (int _i = 0; _i < 2; ++_i) \
;         __builtin_amdgcn_global_load_lds((const unsigned*)((const char*)(gbase) + (voff)[_i]), (PG8_LAS unsigned*)(lds + (bufoff) + ldsw + _i * 8192), 16, 0, 0); } while (0)
; #define PG8_LDA(dst, b, h) do { _Pragma("unroll") for (int m = 0; m < 4; ++m) _Pragma("unroll") for (int k = 0; k < 2; ++k) dst[m][k] = *(const PG8_LAS bf16x8*)(lds + PG8_SA(b, h) + aoff + m * 2048 + k * 1024); } while (0)
; #define PG8_LDB(dst, b, h) do { _Pragma("unroll") for (int n = 0; n < 2; ++n) _Pragma("unroll") for (int k = 0; k < 2; ++k) dst[n][k] = *(const PG8_LAS bf16x8*)(lds + PG8_SB(b, h) + boff + n * 2048 + k * 1024); } while (0)
; #define PG8_BAR __builtin_amdgcn_s_barrier()
;     __host__ __device__ bool next(int i, Unit& u) const {
;         const long L = (long)i * G + c; if (L >= nwg) return false;
;         int wgid = (int)L; { const int q = nwg / NXCD, r = nwg % NXCD, xcd = wgid % NXCD, off = wgid / NXCD; wgid = (xcd < r ? xcd * (q + 1) : r * (q + 1) + (xcd - r) * q) + off; }
;         const int nig = WGM * nN, gid = wgid / nig, fm = gid * WGM, gsz = (nM - fm) < WGM ? (nM - fm) : WGM;
;         u.pm = fm + ((wgid % nig) % gsz); u.pn = (wgid % nig) / gsz; return true;
;     }
; template <class Epi, class Sched, bool ALIGN_EPI = false, bool SP2 = false>
; __device__ __forceinline__ void gemm_phase(PG8_LAS unsigned char* lds, const Gemm g, const Sched& S, const Epi& E) {
;     ...
;         const bool has_next = S.next(ui + 1, nxt);
;         const char* nA = has_next ? (const char*)g.A + (size_t)nxt.pm * tstep : cA; const char* nB = has_next ? (const char*)g.Bt + (size_t)nxt.pn * tstep : cB;
;         for (int t = 0; t < nt; t += 2) {
;             const bool last = (t == nt - 2);
;             const char* a1 = cA + (size_t)(t + 1) * kstepA;
;             const char* a2 = last ? nA : cA + (size_t)(t + 2) * kstepA; const char* b2 = last ? nB : cB + (size_t)(t + 2) * kstep;
;             const char* a3 = a2 + kstepA; const char* b3 = b2 + kstep;
;             if (last && has_next) S.a_ready(nxt);
;             if constexpr (SP2) {
;             PG8_LDB(B0, 0, 0); PG8_LDB(B1, 0, 1); PG8_SCHED; PG8_LDA(At, 0, 0); PG8_STAGE(PG8_SA(1, 1), a1 + hstep, voffA);
;             PG8_WAIT_V(8); PG8_WAIT_L(0); PG8_BAR; PG8_MMA(0, 0, At, B0); PG8_MMA(0, 1, At, B1); PG8_BAR; PG8_SCHED;
.LBB0_406:
	s_add_i32 s51, s52, 1
	s_mul_i32 s4, s51, s15
	s_mul_hi_u32 s5, s51, s14
	s_add_i32 s5, s5, s4
	s_mul_i32 s4, s51, s14
	s_add_u32 s12, s4, s16
	s_addc_u32 s13, s5, s17
	v_cmp_gt_i64_e32 vcc, s[12:13], v[156:157]
	v_cmp_lt_i64_e64 s[4:5], s[12:13], v[154:155]
	s_cbranch_vccnz .LBB0_408
	s_ashr_i32 s8, s12, 31
	s_lshr_b32 s8, s8, 29
	s_add_i32 s8, s12, s8
	s_ashr_i32 s9, s8, 3
	s_and_b32 s8, s8, -8
	s_sub_i32 s8, s12, s8
	s_cmp_lt_i32 s8, 0
	s_cselect_b32 s10, s73, 0x2c0
	s_mul_i32 s8, s8, s10
	s_add_i32 s8, s8, s9
	s_mul_hi_i32 s9, s8, 0x2e8ba2e9
	s_lshr_b32 s10, s9, 31
	s_ashr_i32 s9, s9, 5
	s_add_i32 s9, s9, s10
	s_lshl_b32 s10, s9, 3
	s_sub_i32 s11, 0x100, s10
	s_min_i32 s11, s11, 8
	s_cmp_lg_u32 s11, 8
	s_cbranch_scc1 .Lslowdiv_2
	s_mulk_i32 s9, 0xb0
	s_sub_i32 s9, s8, s9
	s_lshr_b32 s8, s9, 3
	s_and_b32 s9, s9, 7
	s_add_i32 s10, s10, s9
	s_branch .Lfastdiv_done_2
.Lslowdiv_2:
	s_abs_i32 s12, s11
	v_cvt_f32_u32_e32 v2, s12
	s_sub_i32 s18, 0, s12
	s_mulk_i32 s9, 0xb0
	s_sub_i32 s9, s8, s9
	v_rcp_iflag_f32_e32 v2, v2
	s_abs_i32 s8, s9
	s_xor_b32 s13, s9, s11
	s_ashr_i32 s13, s13, 31
	v_mul_f32_e32 v2, 0x4f7ffffe, v2
	v_cvt_u32_f32_e32 v2, v2
	s_nop 0
	v_readfirstlane_b32 s19, v2
	s_mul_i32 s18, s18, s19
	s_mul_hi_u32 s18, s19, s18
	s_add_i32 s19, s19, s18
	s_mul_hi_u32 s18, s8, s19
	s_mul_i32 s19, s18, s12
	s_sub_i32 s8, s8, s19
	s_add_i32 s26, s18, 1
	s_sub_i32 s19, s8, s12
	s_cmp_ge_u32 s8, s12
	s_cselect_b32 s18, s26, s18
	s_cselect_b32 s8, s19, s8
	s_add_i32 s19, s18, 1
	s_cmp_ge_u32 s8, s12
	s_cselect_b32 s8, s19, s18
	s_xor_b32 s8, s8, s13
	s_sub_i32 s8, s8, s13
	s_mul_i32 s11, s8, s11
	s_sub_i32 s9, s9, s11
	s_add_i32 s10, s10, s9
.Lfastdiv_done_2:
.LBB0_408:
	s_ashr_i32 s11, s10, 31
	s_lshl_b64 s[12:13], s[10:11], 19
	s_add_u32 s12, s30, s12
	s_addc_u32 s13, s31, s13
	s_and_b64 s[18:19], s[4:5], exec
	s_cselect_b32 s11, s13, s23
	s_cselect_b32 s53, s12, s22
	s_ashr_i32 s9, s8, 31
	s_lshl_b64 s[18:19], s[8:9], 19
	s_add_u32 s18, s37, s18
	s_addc_u32 s19, s44, s19
	s_and_b64 s[26:27], s[4:5], exec
	s_cselect_b32 s9, s19, s25
	s_cselect_b32 s54, s18, s24
	s_add_u32 s55, s24, 0x100
	s_addc_u32 s56, s25, 0
	s_mov_b32 s57, -2
	s_add_u32 s24, s22, 0x8000
	s_addc_u32 s25, s23, 0
	s_cmp_eq_u32 s57, 12
	s_cselect_b32 s42, s53, s24
	s_cselect_b32 s43, s11, s25
	s_cselect_b32 s40, s54, s55
	s_cselect_b32 s41, s9, s56
	s_add_u32 s26, s42, 0x4000
	s_addc_u32 s27, s43, 0
	v_add_u32_e32 v145, s76, v142
	s_add_i32 s58, 0, 0x14000
	ds_read_b128 v[146:149], v145
	ds_read_b128 v[150:153], v145 offset:1024
	ds_read_b128 v[160:163], v145 offset:2048
	ds_read_b128 v[164:167], v145 offset:3072
	v_add_u32_e32 v145, s58, v142
	ds_read_b128 v[168:171], v145
	ds_read_b128 v[172:175], v145 offset:1024
	ds_read_b128 v[176:179], v145 offset:2048
	ds_read_b128 v[180:183], v145 offset:3072
	v_lshl_add_u64 v[230:231], s[22:23], 0, v[140:141]
	s_add_i32 m0, s45, 0xc000
	ds_read_b128 v[184:187], v144
	ds_read_b128 v[188:191], v144 offset:1024
	ds_read_b128 v[206:209], v144 offset:2048
	ds_read_b128 v[210:213], v144 offset:3072
	ds_read_b128 v[214:217], v144 offset:4096
	ds_read_b128 v[218:221], v144 offset:5120
	ds_read_b128 v[222:225], v144 offset:6144
	ds_read_b128 v[226:229], v144 offset:7168
	global_load_lds_dwordx4 v[230:231], off
	v_lshl_add_u64 v[230:231], s[22:23], 0, v[138:139]
	s_add_i32 m0, s45, 0xe000
	s_nop 0
	global_load_lds_dwordx4 v[230:231], off
	s_waitcnt vmcnt(8)
	s_waitcnt lgkmcnt(0)
	s_barrier
	v_mfma_f32_16x16x32_bf16 v[126:129], v[146:149], v[184:187], 0
	v_mfma_f32_16x16x32_bf16 v[126:129], v[150:153], v[188:191], v[126:129]
	v_mfma_f32_16x16x32_bf16 v[118:121], v[164:167], v[188:191], 0
	v_mfma_f32_16x16x32_bf16 v[118:121], v[160:163], v[184:187], v[118:121]
	v_mfma_f32_16x16x32_bf16 v[102:105], v[160:163], v[206:209], 0
	v_mfma_f32_16x16x32_bf16 v[102:105], v[164:167], v[210:213], v[102:105]
	v_mfma_f32_16x16x32_bf16 v[110:113], v[150:153], v[210:213], 0
	v_mfma_f32_16x16x32_bf16 v[110:113], v[146:149], v[206:209], v[110:113]
	v_mfma_f32_16x16x32_bf16 v[94:97], v[146:149], v[214:217], 0
	v_mfma_f32_16x16x32_bf16 v[94:97], v[150:153], v[218:221], v[94:97]
	v_mfma_f32_16x16x32_bf16 v[86:89], v[164:167], v[218:221], 0
	v_mfma_f32_16x16x32_bf16 v[86:89], v[160:163], v[214:217], v[86:89]
	v_mfma_f32_16x16x32_bf16 v[70:73], v[160:163], v[222:225], 0
	v_mfma_f32_16x16x32_bf16 v[70:73], v[164:167], v[226:229], v[70:73]
	v_mfma_f32_16x16x32_bf16 v[78:81], v[150:153], v[226:229], 0
	v_mfma_f32_16x16x32_bf16 v[78:81], v[146:149], v[222:225], v[78:81]
	v_mfma_f32_16x16x32_bf16 v[122:125], v[168:171], v[184:187], 0
	v_mfma_f32_16x16x32_bf16 v[122:125], v[172:175], v[188:191], v[122:125]
	v_mfma_f32_16x16x32_bf16 v[114:117], v[180:183], v[188:191], 0
	v_mfma_f32_16x16x32_bf16 v[114:117], v[176:179], v[184:187], v[114:117]
	v_mfma_f32_16x16x32_bf16 v[98:101], v[176:179], v[206:209], 0
	v_mfma_f32_16x16x32_bf16 v[98:101], v[180:183], v[210:213], v[98:101]
	v_mfma_f32_16x16x32_bf16 v[106:109], v[172:175], v[210:213], 0
	v_mfma_f32_16x16x32_bf16 v[106:109], v[168:171], v[206:209], v[106:109]
	v_mfma_f32_16x16x32_bf16 v[90:93], v[168:171], v[214:217], 0
	v_mfma_f32_16x16x32_bf16 v[90:93], v[172:175], v[218:221], v[90:93]
	v_mfma_f32_16x16x32_bf16 v[82:85], v[180:183], v[218:221], 0
	v_mfma_f32_16x16x32_bf16 v[82:85], v[176:179], v[214:217], v[82:85]
	v_mfma_f32_16x16x32_bf16 v[66:69], v[176:179], v[222:225], 0
	v_mfma_f32_16x16x32_bf16 v[66:69], v[180:183], v[226:229], v[66:69]
	v_mfma_f32_16x16x32_bf16 v[74:77], v[172:175], v[226:229], 0
	v_mfma_f32_16x16x32_bf16 v[74:77], v[168:171], v[222:225], v[74:77]
	s_barrier
; #define PG8_STAGE(bufoff, gbase, voff) do { _Pragma("unroll") for (int _i = 0; _i < 2; ++_i) \
;         __builtin_amdgcn_global_load_lds((const unsigned*)((const char*)(gbase) + (voff)[_i]), (PG8_LAS unsigned*)(lds + (bufoff) + ldsw + _i * 8192), 16, 0, 0); } while (0)
; #define PG8_LDA(dst, b, h) do { _Pragma("unroll") for (int m = 0; m < 4; ++m) _Pragma("unroll") for (int k = 0; k < 2; ++k) dst[m][k] = *(const PG8_LAS bf16x8*)(lds + PG8_SA(b, h) + aoff + m * 2048 + k * 1024); } while (0)
; #define PG8_LDB(dst, b, h) do { _Pragma("unroll") for (int n = 0; n < 2; ++n) _Pragma("unroll") for (int k = 0; k < 2; ++k) dst[n][k] = *(const PG8_LAS bf16x8*)(lds + PG8_SB(b, h) + boff + n * 2048 + k * 1024); } while (0)
; #define PG8_MMA(ai, bj, At, Bt) do { __builtin_amdgcn_s_setprio(1); _Pragma("unroll") for (int m = 0; m < 4; ++m) _Pragma("unroll") for (int n = 0; n < 2; ++n) _Pragma("unroll") for (int k = 0; k < 2; ++k) \
;         acc[ai][bj][m][n] = __builtin_amdgcn_mfma_f32_16x16x32_bf16(Bt[n][k], At[m][k], acc[ai][bj][m][n], 0, 0, 0); __builtin_amdgcn_s_setprio(0); } while (0)
; #define PG8_WAIT_V(n) asm volatile("s_waitcnt vmcnt(" #n ")" ::: "memory")
; #define PG8_WAIT_L(n) asm volatile("s_waitcnt lgkmcnt(" #n ")" ::: "memory")
; #define PG8_BAR __builtin_amdgcn_s_barrier()
; #define PG8_SCHED __builtin_amdgcn_sched_barrier(0)
; template <class Epi, class Sched, bool ALIGN_EPI = false, bool SP2 = false>
; __device__ __forceinline__ void gemm_phase(PG8_LAS unsigned char* lds, const Gemm g, const Sched& S, const Epi& E) {
;     ...
;             PG8_LDA(At, 0, 1); PG8_STAGE(PG8_SB(0, 0), b2, voffB); PG8_STAGE(PG8_SB(0, 1), b2 + hstep, voffB); PG8_STAGE(PG8_SA(0, 0), a2, voffA);
;             PG8_WAIT_V(8); PG8_WAIT_L(0); PG8_BAR; PG8_MMA(1, 0, At, B0); PG8_MMA(1, 1, At, B1); PG8_BAR; PG8_SCHED;
;             PG8_LDB(B0, 1, 0); PG8_LDB(B1, 1, 1); PG8_SCHED; PG8_LDA(At, 1, 0); PG8_STAGE(PG8_SA(0, 1), a2 + hstep, voffA);
;             PG8_WAIT_V(8); PG8_WAIT_L(0); PG8_BAR; PG8_MMA(0, 0, At, B0); PG8_MMA(0, 1, At, B1); PG8_BAR; PG8_SCHED;
	s_add_i32 s22, s76, s29
	v_lshl_add_u64 v[230:231], s[40:41], 0, v[0:1]
	s_mov_b32 m0, s22
	ds_read_b128 v[184:187], v144 offset:16384
	ds_read_b128 v[188:191], v144 offset:17408
	ds_read_b128 v[206:209], v144 offset:18432
	ds_read_b128 v[210:213], v144 offset:19456
	ds_read_b128 v[214:217], v144 offset:20480
	ds_read_b128 v[218:221], v144 offset:21504
	ds_read_b128 v[222:225], v144 offset:22528
	ds_read_b128 v[226:229], v144 offset:23552
	global_load_lds_dwordx4 v[230:231], off
	s_add_i32 m0, s22, 0x2000
	s_add_u32 s22, s40, 0x40000
	v_lshl_add_u64 v[232:233], s[40:41], 0, v[130:131]
	s_addc_u32 s23, s41, 0
	s_add_i32 s58, s58, s29
	global_load_lds_dwordx4 v[232:233], off
	v_lshl_add_u64 v[234:235], s[22:23], 0, v[0:1]
	s_mov_b32 m0, s58
	s_nop 0
	global_load_lds_dwordx4 v[234:235], off
	v_lshl_add_u64 v[234:235], s[22:23], 0, v[130:131]
	s_add_i32 m0, s58, 0x2000
	s_nop 0
	global_load_lds_dwordx4 v[234:235], off
	v_lshl_add_u64 v[234:235], s[42:43], 0, v[134:135]
	s_mov_b32 m0, s45
	s_nop 0
	global_load_lds_dwordx4 v[234:235], off
	v_lshl_add_u64 v[234:235], s[42:43], 0, v[132:133]
	s_mov_b32 m0, s46
	s_nop 0
	global_load_lds_dwordx4 v[234:235], off
	s_waitcnt vmcnt(8)
	s_waitcnt lgkmcnt(0)
	s_barrier
	v_mfma_f32_16x16x32_bf16 v[62:65], v[146:149], v[184:187], 0
	v_mfma_f32_16x16x32_bf16 v[62:65], v[150:153], v[188:191], v[62:65]
	v_mfma_f32_16x16x32_bf16 v[54:57], v[164:167], v[188:191], 0
	v_mfma_f32_16x16x32_bf16 v[54:57], v[160:163], v[184:187], v[54:57]
	v_mfma_f32_16x16x32_bf16 v[38:41], v[160:163], v[206:209], 0
	v_mfma_f32_16x16x32_bf16 v[38:41], v[164:167], v[210:213], v[38:41]
	v_mfma_f32_16x16x32_bf16 v[46:49], v[150:153], v[210:213], 0
	v_mfma_f32_16x16x32_bf16 v[46:49], v[146:149], v[206:209], v[46:49]
	v_mfma_f32_16x16x32_bf16 v[30:33], v[146:149], v[214:217], 0
	v_mfma_f32_16x16x32_bf16 v[30:33], v[150:153], v[218:221], v[30:33]
	v_mfma_f32_16x16x32_bf16 v[22:25], v[164:167], v[218:221], 0
	v_mfma_f32_16x16x32_bf16 v[22:25], v[160:163], v[214:217], v[22:25]
	v_mfma_f32_16x16x32_bf16 v[6:9], v[160:163], v[222:225], 0
	v_mfma_f32_16x16x32_bf16 v[6:9], v[164:167], v[226:229], v[6:9]
	v_mfma_f32_16x16x32_bf16 v[14:17], v[150:153], v[226:229], 0
	v_mfma_f32_16x16x32_bf16 v[14:17], v[146:149], v[222:225], v[14:17]
	v_mfma_f32_16x16x32_bf16 v[58:61], v[168:171], v[184:187], 0
	v_mfma_f32_16x16x32_bf16 v[58:61], v[172:175], v[188:191], v[58:61]
	v_mfma_f32_16x16x32_bf16 v[50:53], v[180:183], v[188:191], 0
	v_mfma_f32_16x16x32_bf16 v[50:53], v[176:179], v[184:187], v[50:53]
	v_mfma_f32_16x16x32_bf16 v[34:37], v[176:179], v[206:209], 0
	v_mfma_f32_16x16x32_bf16 v[34:37], v[180:183], v[210:213], v[34:37]
	v_mfma_f32_16x16x32_bf16 v[42:45], v[172:175], v[210:213], 0
	v_mfma_f32_16x16x32_bf16 v[42:45], v[168:171], v[206:209], v[42:45]
	v_mfma_f32_16x16x32_bf16 v[26:29], v[168:171], v[214:217], 0
	v_mfma_f32_16x16x32_bf16 v[26:29], v[172:175], v[218:221], v[26:29]
	v_mfma_f32_16x16x32_bf16 v[18:21], v[180:183], v[218:221], 0
	v_mfma_f32_16x16x32_bf16 v[18:21], v[176:179], v[214:217], v[18:21]
	v_mfma_f32_16x16x32_bf16 v[2:5], v[176:179], v[222:225], 0
	v_mfma_f32_16x16x32_bf16 v[2:5], v[180:183], v[226:229], v[2:5]
	v_mfma_f32_16x16x32_bf16 v[10:13], v[172:175], v[226:229], 0
	v_mfma_f32_16x16x32_bf16 v[10:13], v[168:171], v[222:225], v[10:13]
	s_barrier
	s_add_i32 s58, 0, 0x18000
	v_add_u32_e32 v145, s58, v142
	s_add_i32 s59, 0, 0x1c000
	ds_read_b128 v[146:149], v145
	ds_read_b128 v[150:153], v145 offset:1024
	ds_read_b128 v[160:163], v145 offset:2048
	ds_read_b128 v[164:167], v145 offset:3072
	v_add_u32_e32 v145, s59, v142
	ds_read_b128 v[168:171], v145
	ds_read_b128 v[172:175], v145 offset:1024
	ds_read_b128 v[176:179], v145 offset:2048
	ds_read_b128 v[180:183], v145 offset:3072
	s_add_u32 s22, s42, 0x40000
	s_addc_u32 s23, s43, 0
	s_mov_b32 m0, s47
	v_lshl_add_u64 v[234:235], s[22:23], 0, v[134:135]
	ds_read_b128 v[184:187], v144 offset:32768
	ds_read_b128 v[188:191], v144 offset:33792
	ds_read_b128 v[206:209], v144 offset:34816
	ds_read_b128 v[210:213], v144 offset:35840
	ds_read_b128 v[214:217], v144 offset:36864
	ds_read_b128 v[218:221], v144 offset:37888
	ds_read_b128 v[222:225], v144 offset:38912
	ds_read_b128 v[226:229], v144 offset:39936
	global_load_lds_dwordx4 v[234:235], off
	v_lshl_add_u64 v[234:235], s[22:23], 0, v[132:133]
	s_mov_b32 m0, s48
	s_nop 0
	global_load_lds_dwordx4 v[234:235], off
	s_waitcnt vmcnt(8)
	s_waitcnt lgkmcnt(0)
	s_barrier
; #define PG8_STAGE(bufoff, gbase, voff) do { _Pragma("unroll") for (int _i = 0; _i < 2; ++_i) \
;         __builtin_amdgcn_global_load_lds((const unsigned*)((const char*)(gbase) + (voff)[_i]), (PG8_LAS unsigned*)(lds + (bufoff) + ldsw + _i * 8192), 16, 0, 0); } while (0)
; #define PG8_LDA(dst, b, h) do { _Pragma("unroll") for (int m = 0; m < 4; ++m) _Pragma("unroll") for (int k = 0; k < 2; ++k) dst[m][k] = *(const PG8_LAS bf16x8*)(lds + PG8_SA(b, h) + aoff + m * 2048 + k * 1024); } while (0)
; #define PG8_MMA(ai, bj, At, Bt) do { __builtin_amdgcn_s_setprio(1); _Pragma("unroll") for (int m = 0; m < 4; ++m) _Pragma("unroll") for (int n = 0; n < 2; ++n) _Pragma("unroll") for (int k = 0; k < 2; ++k) \
;         acc[ai][bj][m][n] = __builtin_amdgcn_mfma_f32_16x16x32_bf16(Bt[n][k], At[m][k], acc[ai][bj][m][n], 0, 0, 0); __builtin_amdgcn_s_setprio(0); } while (0)
; #define PG8_WAIT_V(n) asm volatile("s_waitcnt vmcnt(" #n ")" ::: "memory")
; #define PG8_WAIT_L(n) asm volatile("s_waitcnt lgkmcnt(" #n ")" ::: "memory")
; #define PG8_BAR __builtin_amdgcn_s_barrier()
; #define PG8_SCHED __builtin_amdgcn_sched_barrier(0)
; template <class Epi, class Sched, bool ALIGN_EPI = false, bool SP2 = false>
; __device__ __forceinline__ void gemm_phase(PG8_LAS unsigned char* lds, const Gemm g, const Sched& S, const Epi& E) {
;     ...
;             PG8_WAIT_V(8); PG8_WAIT_L(0); PG8_BAR; PG8_MMA(0, 0, At, B0); PG8_MMA(0, 1, At, B1); PG8_BAR; PG8_SCHED;
;             PG8_LDA(At, 1, 1); PG8_STAGE(PG8_SB(1, 0), b3, voffB); PG8_STAGE(PG8_SB(1, 1), b3 + hstep, voffB); PG8_STAGE(PG8_SA(1, 0), a3, voffA);
;             PG8_WAIT_V(8); PG8_WAIT_L(0); PG8_BAR; PG8_MMA(1, 0, At, B0); PG8_MMA(1, 1, At, B1); PG8_BAR; PG8_SCHED;
	v_mfma_f32_16x16x32_bf16 v[126:129], v[146:149], v[184:187], v[126:129]
	v_mfma_f32_16x16x32_bf16 v[126:129], v[150:153], v[188:191], v[126:129]
	v_mfma_f32_16x16x32_bf16 v[118:121], v[164:167], v[188:191], v[118:121]
	v_mfma_f32_16x16x32_bf16 v[118:121], v[160:163], v[184:187], v[118:121]
	v_mfma_f32_16x16x32_bf16 v[102:105], v[160:163], v[206:209], v[102:105]
	v_mfma_f32_16x16x32_bf16 v[102:105], v[164:167], v[210:213], v[102:105]
	v_mfma_f32_16x16x32_bf16 v[110:113], v[150:153], v[210:213], v[110:113]
	v_mfma_f32_16x16x32_bf16 v[110:113], v[146:149], v[206:209], v[110:113]
	v_mfma_f32_16x16x32_bf16 v[94:97], v[146:149], v[214:217], v[94:97]
	v_mfma_f32_16x16x32_bf16 v[94:97], v[150:153], v[218:221], v[94:97]
	v_mfma_f32_16x16x32_bf16 v[86:89], v[164:167], v[218:221], v[86:89]
	v_mfma_f32_16x16x32_bf16 v[86:89], v[160:163], v[214:217], v[86:89]
	v_mfma_f32_16x16x32_bf16 v[70:73], v[160:163], v[222:225], v[70:73]
	v_mfma_f32_16x16x32_bf16 v[70:73], v[164:167], v[226:229], v[70:73]
	v_mfma_f32_16x16x32_bf16 v[78:81], v[150:153], v[226:229], v[78:81]
	v_mfma_f32_16x16x32_bf16 v[78:81], v[146:149], v[222:225], v[78:81]
	v_mfma_f32_16x16x32_bf16 v[122:125], v[168:171], v[184:187], v[122:125]
	v_mfma_f32_16x16x32_bf16 v[122:125], v[172:175], v[188:191], v[122:125]
	v_mfma_f32_16x16x32_bf16 v[114:117], v[180:183], v[188:191], v[114:117]
	v_mfma_f32_16x16x32_bf16 v[114:117], v[176:179], v[184:187], v[114:117]
	v_mfma_f32_16x16x32_bf16 v[98:101], v[176:179], v[206:209], v[98:101]
	v_mfma_f32_16x16x32_bf16 v[98:101], v[180:183], v[210:213], v[98:101]
	v_mfma_f32_16x16x32_bf16 v[106:109], v[172:175], v[210:213], v[106:109]
	v_mfma_f32_16x16x32_bf16 v[106:109], v[168:171], v[206:209], v[106:109]
	v_mfma_f32_16x16x32_bf16 v[90:93], v[168:171], v[214:217], v[90:93]
	v_mfma_f32_16x16x32_bf16 v[90:93], v[172:175], v[218:221], v[90:93]
	v_mfma_f32_16x16x32_bf16 v[82:85], v[180:183], v[218:221], v[82:85]
	v_mfma_f32_16x16x32_bf16 v[82:85], v[176:179], v[214:217], v[82:85]
	v_mfma_f32_16x16x32_bf16 v[66:69], v[176:179], v[222:225], v[66:69]
	v_mfma_f32_16x16x32_bf16 v[66:69], v[180:183], v[226:229], v[66:69]
	v_mfma_f32_16x16x32_bf16 v[74:77], v[172:175], v[226:229], v[74:77]
	v_mfma_f32_16x16x32_bf16 v[74:77], v[168:171], v[222:225], v[74:77]
	s_barrier
	s_add_i32 s22, s58, s29
	v_lshl_add_u64 v[230:231], v[230:231], 0, s[38:39]
	s_mov_b32 m0, s22
	ds_read_b128 v[184:187], v144 offset:49152
	ds_read_b128 v[188:191], v144 offset:50176
	ds_read_b128 v[206:209], v144 offset:51200
	ds_read_b128 v[210:213], v144 offset:52224
	ds_read_b128 v[214:217], v144 offset:53248
	ds_read_b128 v[218:221], v144 offset:54272
	ds_read_b128 v[222:225], v144 offset:55296
	ds_read_b128 v[226:229], v144 offset:56320
	global_load_lds_dwordx4 v[230:231], off
	s_add_i32 m0, s22, 0x2000
	s_add_u32 s22, s40, 0x40080
	v_lshl_add_u64 v[230:231], v[232:233], 0, s[38:39]
	s_addc_u32 s23, s41, 0
	s_add_i32 s40, s59, s29
	global_load_lds_dwordx4 v[230:231], off
	v_lshl_add_u64 v[230:231], s[22:23], 0, v[0:1]
	s_mov_b32 m0, s40
	s_nop 0
	global_load_lds_dwordx4 v[230:231], off
	v_lshl_add_u64 v[230:231], s[22:23], 0, v[130:131]
	s_add_i32 m0, s40, 0x2000
	s_nop 0
	global_load_lds_dwordx4 v[230:231], off
	v_lshl_add_u64 v[230:231], s[26:27], 0, v[134:135]
	s_mov_b32 m0, s49
	s_nop 0
	global_load_lds_dwordx4 v[230:231], off
	v_lshl_add_u64 v[230:231], s[26:27], 0, v[132:133]
	s_mov_b32 m0, s50
	s_nop 0
	global_load_lds_dwordx4 v[230:231], off
	s_waitcnt vmcnt(8)
	s_waitcnt lgkmcnt(0)
	s_barrier
	v_mfma_f32_16x16x32_bf16 v[62:65], v[146:149], v[184:187], v[62:65]
	v_mfma_f32_16x16x32_bf16 v[62:65], v[150:153], v[188:191], v[62:65]
	v_mfma_f32_16x16x32_bf16 v[54:57], v[164:167], v[188:191], v[54:57]
	v_mfma_f32_16x16x32_bf16 v[54:57], v[160:163], v[184:187], v[54:57]
	v_mfma_f32_16x16x32_bf16 v[38:41], v[160:163], v[206:209], v[38:41]
	v_mfma_f32_16x16x32_bf16 v[38:41], v[164:167], v[210:213], v[38:41]
	v_mfma_f32_16x16x32_bf16 v[46:49], v[150:153], v[210:213], v[46:49]
	v_mfma_f32_16x16x32_bf16 v[46:49], v[146:149], v[206:209], v[46:49]
	v_mfma_f32_16x16x32_bf16 v[30:33], v[146:149], v[214:217], v[30:33]
	v_mfma_f32_16x16x32_bf16 v[30:33], v[150:153], v[218:221], v[30:33]
	v_mfma_f32_16x16x32_bf16 v[22:25], v[164:167], v[218:221], v[22:25]
	v_mfma_f32_16x16x32_bf16 v[22:25], v[160:163], v[214:217], v[22:25]
	v_mfma_f32_16x16x32_bf16 v[6:9], v[160:163], v[222:225], v[6:9]
	v_mfma_f32_16x16x32_bf16 v[6:9], v[164:167], v[226:229], v[6:9]
	v_mfma_f32_16x16x32_bf16 v[14:17], v[150:153], v[226:229], v[14:17]
	v_mfma_f32_16x16x32_bf16 v[14:17], v[146:149], v[222:225], v[14:17]
	v_mfma_f32_16x16x32_bf16 v[58:61], v[168:171], v[184:187], v[58:61]
	v_mfma_f32_16x16x32_bf16 v[58:61], v[172:175], v[188:191], v[58:61]
	v_mfma_f32_16x16x32_bf16 v[50:53], v[180:183], v[188:191], v[50:53]
	v_mfma_f32_16x16x32_bf16 v[50:53], v[176:179], v[184:187], v[50:53]
	v_mfma_f32_16x16x32_bf16 v[34:37], v[176:179], v[206:209], v[34:37]
	v_mfma_f32_16x16x32_bf16 v[34:37], v[180:183], v[210:213], v[34:37]
	v_mfma_f32_16x16x32_bf16 v[42:45], v[172:175], v[210:213], v[42:45]
	v_mfma_f32_16x16x32_bf16 v[42:45], v[168:171], v[206:209], v[42:45]
	v_mfma_f32_16x16x32_bf16 v[26:29], v[168:171], v[214:217], v[26:29]
	v_mfma_f32_16x16x32_bf16 v[26:29], v[172:175], v[218:221], v[26:29]
	v_mfma_f32_16x16x32_bf16 v[18:21], v[180:183], v[218:221], v[18:21]
	v_mfma_f32_16x16x32_bf16 v[18:21], v[176:179], v[214:217], v[18:21]
	v_mfma_f32_16x16x32_bf16 v[2:5], v[176:179], v[222:225], v[2:5]
	v_mfma_f32_16x16x32_bf16 v[2:5], v[180:183], v[226:229], v[2:5]
	v_mfma_f32_16x16x32_bf16 v[10:13], v[172:175], v[226:229], v[10:13]
	v_mfma_f32_16x16x32_bf16 v[10:13], v[168:171], v[222:225], v[10:13]
	s_barrier
	s_add_i32 s57, s57, 2
	s_add_u32 s55, s55, 0x100
	s_addc_u32 s56, s56, 0
	s_cmp_gt_u32 s57, 13
	s_mov_b64 s[22:23], s[24:25]
	s_cbranch_scc1 .Lpeel_exit_2
